# cmp phase: the four heads' Q fragments preloaded once per unit into register banks rotated with v_swap (no per-head / per-chunk global round trips)
# baseline (speedup 1.0000x reference)
; #define LAS __attribute__((address_space(3)))
; __device__ __forceinline__ void cmp_phase(LAS unsigned char* lds, const bf16_t* __restrict__ P, const bf16_t* __restrict__ Kc, const bf16_t* __restrict__ Vc,
;                                           bf16_t* __restrict__ ocmp, unsigned long long* __restrict__ mask, int G, const int wave0) {
;     ...
;         const int b = unit >> 5, g = (unit >> 4) & 1, kq = (unit >> 1) & 7, hq = unit & 1, bg = b * 2 + g;
;         const int qb = (wid < 4) ? (15 - kq) : kq;
;         __syncthreads();
; #pragma unroll
;         for (int i = 0; i < 4; ++i) {
;             const int c = tid + 512 * i, row = c >> 3, ch = c & 7;
;             const u32x4 kv = *(const u32x4*)(Kc + (size_t)(bg * 256 + row) * 64 + ch * 8);
;             const u32x4 vv = *(const u32x4*)(Vc + (size_t)(bg * 256 + row) * 64 + ch * 8);
;             *(LAS u32x4*)(lds + row * KSTR + ch * 16) = kv;
;             *(LAS u32x4*)(lds + VOFFC + (ch >> 2) * 16384 + row * 64 + (ch & 3) * 16) = vv;
;         }
;         __syncthreads();
;         const int tw0 = qb * 256 + hq * 128 + 32 * (wid & 3), tq = tw0 + r32;
;         const int nch = ((tw0 >> 4) >> 6) + 1;
;         const size_t row = (size_t)b * SEQ + tq;
;         LAS float* mi = (LAS float*)(lds + MI_OFF + wid * 1024);
;         LAS float* sc = (LAS float*)(lds + SC_OFF + wid * (32 * 65 * 4) + r32 * (65 * 4));
;     ...
;                     for (int ds = 0; ds < 4; ++ds) qf[ds] = *(const bf16x8*)(P + row * NPJ + C_NQ + head * 64 + 16 * ds + 8 * hi);
.LBB0_761:
	s_ashr_i32 s4, s3, 5
	s_bfe_u32 s6, s3, 0x10004
	s_lshl_b32 s2, s4, 1
	s_or_b32 s8, s2, s6
	s_mov_b32 s2, s8
	v_mov_b32_e32 v96, v246
	v_writelane_b32 v255, s2, 5
	s_waitcnt vmcnt(0)
	v_lshlrev_b32_e32 v40, 4, v96
	v_writelane_b32 v255, s3, 6
	s_lshl_b32 s2, s8, 8
	v_readlane_b32 s8, v254, 56
	v_add_u32_e32 v8, 0x200, v96
	v_add_u32_e32 v16, 0x400, v96
	s_waitcnt lgkmcnt(1)
	v_add_u32_e32 v28, 0x600, v96
	v_and_b32_e32 v214, 0x70, v40
	v_readlane_b32 s9, v254, 57
	v_ashrrev_i32_e32 v33, 3, v96
	v_ashrrev_i32_e32 v38, 3, v8
	v_ashrrev_i32_e32 v41, 3, v16
	v_ashrrev_i32_e32 v42, 3, v28
	v_lshl_add_u64 v[24:25], s[8:9], 0, v[214:215]
	v_readlane_b32 s8, v254, 58
	v_add_u32_e32 v0, s2, v33
	v_add_u32_e32 v8, s2, v38
	v_add_u32_e32 v16, s2, v41
	v_add_u32_e32 v28, s2, v42
	v_readlane_b32 s9, v254, 59
	v_ashrrev_i32_e32 v1, 31, v0
	v_ashrrev_i32_e32 v9, 31, v8
	v_ashrrev_i32_e32 v17, 31, v16
	v_ashrrev_i32_e32 v29, 31, v28
	v_lshl_add_u64 v[26:27], s[8:9], 0, v[214:215]
	v_lshlrev_b64 v[0:1], 7, v[0:1]
	v_lshlrev_b64 v[8:9], 7, v[8:9]
	v_lshlrev_b64 v[16:17], 7, v[16:17]
	v_lshlrev_b64 v[28:29], 7, v[28:29]
	v_lshl_add_u64 v[2:3], v[24:25], 0, v[0:1]
	v_lshl_add_u64 v[4:5], v[26:27], 0, v[0:1]
	v_lshl_add_u64 v[10:11], v[24:25], 0, v[8:9]
	v_lshl_add_u64 v[12:13], v[26:27], 0, v[8:9]
	v_lshl_add_u64 v[18:19], v[24:25], 0, v[16:17]
	v_lshl_add_u64 v[20:21], v[26:27], 0, v[16:17]
	v_lshl_add_u64 v[24:25], v[24:25], 0, v[28:29]
	v_lshl_add_u64 v[28:29], v[26:27], 0, v[28:29]
	s_barrier
	global_load_dwordx4 v[0:3], v[2:3], off
	s_nop 0
	global_load_dwordx4 v[4:7], v[4:5], off
	s_nop 0
	global_load_dwordx4 v[8:11], v[10:11], off
	s_nop 0
	global_load_dwordx4 v[12:15], v[12:13], off
	s_nop 0
	global_load_dwordx4 v[16:19], v[18:19], off
	s_nop 0
	global_load_dwordx4 v[20:23], v[20:21], off
	s_nop 0
	global_load_dwordx4 v[24:27], v[24:25], off
	s_waitcnt lgkmcnt(0)
	global_load_dwordx4 v[28:31], v[28:29], off
	s_lshl_b32 s5, s3, 7
	v_lshlrev_b32_e32 v32, 12, v96
	s_and_b32 s7, s5, 0x700
	v_and_b32_e32 v34, 0x4000, v32
	v_and_b32_e32 v35, 48, v40
	v_add_u32_e32 v32, 0, v214
	s_lshr_b32 s8, s3, 4
	v_writelane_b32 v255, s3, 7
	s_xor_b32 s9, s7, 0xf00
	v_add3_u32 v44, 0, v34, v35
	v_mad_u64_u32 v[34:35], s[2:3], v33, s84, v[32:33]
	v_mad_u64_u32 v[36:37], s[2:3], v38, s84, v[32:33]
	s_and_b64 s[2:3], s[66:67], exec
	v_lshl_add_u32 v35, v33, 6, v44
	v_lshl_add_u32 v37, v38, 6, v44
	v_mad_u64_u32 v[38:39], s[2:3], v41, s84, v[32:33]
	v_mad_u64_u32 v[32:33], s[2:3], v42, s84, v[32:33]
	s_cselect_b32 s7, s9, s7
	s_and_b32 s2, s5, 0x80
	v_readlane_b32 s3, v253, 13
	s_or_b32 s2, s3, s2
	v_and_b32_e32 v81, 31, v96
	s_or_b32 s87, s2, s7
	s_ashr_i32 s5, s4, 31
	v_readlane_b32 s10, v254, 48
	v_or_b32_e32 v82, s87, v81
	s_lshl_b64 s[2:3], s[4:5], 12
	v_readlane_b32 s11, v254, 49
	v_lshl_add_u32 v39, v41, 6, v44
	v_lshl_add_u32 v33, v42, 6, v44
	v_bfe_u32 v80, v96, 5, 1
	v_lshlrev_b32_e32 v84, 4, v80
	v_mov_b32_e32 v85, v215
	v_and_b32_e32 v43, 63, v96
	v_mad_u32_u24 v99, v81, s84, v84
	s_waitcnt vmcnt(7)
	ds_write_b128 v34, v[0:3]
	s_waitcnt vmcnt(6)
	ds_write_b128 v35, v[4:7] offset:36864
	s_waitcnt vmcnt(5)
	ds_write_b128 v36, v[8:11]
	s_waitcnt vmcnt(4)
	ds_write_b128 v37, v[12:15] offset:36864
	s_waitcnt vmcnt(3)
	ds_write_b128 v38, v[16:19]
	s_waitcnt vmcnt(2)
	ds_write_b128 v39, v[20:23] offset:36864
	s_waitcnt vmcnt(1)
	ds_write_b128 v32, v[24:27]
	s_waitcnt vmcnt(0)
	ds_write_b128 v33, v[28:31] offset:36864
	v_or_b32_e32 v0, s2, v82
	v_mov_b64_e32 v[2:3], s[10:11]
	v_mad_u64_u32 v[2:3], s[10:11], v0, s65, v[2:3]
	v_mov_b32_e32 v4, 0x1400
	v_mad_i32_i24 v3, s3, v4, v3
	v_lshl_add_u64 v[86:87], v[2:3], 0, v[84:85]
	v_lshlrev_b32_e32 v85, 3, v81
	v_readlane_b32 s2, v253, 6
	v_mov_b32_e32 v1, s3
	v_lshlrev_b64 v[0:1], 10, v[0:1]
	v_add_u32_e32 v98, s2, v85
	v_readlane_b32 s2, v254, 60
	v_readlane_b32 s3, v254, 61
	v_lshlrev_b32_e32 v2, 1, v96
	v_lshlrev_b32_e32 v3, 3, v96
	v_and_b32_e32 v5, 0xc0, v40
	v_lshl_add_u64 v[88:89], s[2:3], 0, v[0:1]
	v_cmp_gt_u32_e64 s[2:3], 32, v43
	v_lshlrev_b32_e32 v4, 3, v80
	v_and_b32_e32 v2, 32, v2
	v_and_b32_e32 v3, 24, v3
	v_cndmask_b32_e64 v0, 24, 16, s[2:3]
	s_and_b32 s11, s7, 0xc00
	v_lshl_or_b32 v1, v80, 8, v5
	s_lshr_b32 s86, s7, 10
	s_add_i32 s5, s87, 0xfffffbf1
	v_lshlrev_b32_e32 v83, 6, v80
	v_subrev_u32_e32 v97, 31, v82
	s_mov_b32 s9, 0
	s_lshl_b32 s10, s6, 8
	v_writelane_b32 v255, s7, 9
	s_addk_i32 s11, 0x400
	v_add_u32_e32 v100, 0, v99
	v_or3_b32 v101, v1, v2, v3
	v_lshlrev_b32_e32 v214, 1, v4
	v_lshlrev_b32_e32 v90, 1, v0
	s_mov_b32 s80, s10
	v_lshl_add_u64 v[166:167], s[80:81], 1, v[86:87]
	global_load_dwordx4 v[130:133], v[166:167], off offset:2752
	global_load_dwordx4 v[134:137], v[166:167], off offset:2784
	global_load_dwordx4 v[138:141], v[166:167], off offset:2816
	global_load_dwordx4 v[142:145], v[166:167], off offset:2848
	global_load_dwordx4 v[146:149], v[166:167], off offset:2368
	global_load_dwordx4 v[150:153], v[166:167], off offset:2400
	global_load_dwordx4 v[154:157], v[166:167], off offset:2432
	global_load_dwordx4 v[158:161], v[166:167], off offset:2464
	global_load_dwordx4 v[200:203], v[166:167], off offset:2496
	global_load_dwordx4 v[204:207], v[166:167], off offset:2528
	global_load_dwordx4 v[208:211], v[166:167], off offset:2560
	global_load_dwordx4 v[216:219], v[166:167], off offset:2592
	global_load_dwordx4 v[220:223], v[166:167], off offset:2624
	global_load_dwordx4 v[224:227], v[166:167], off offset:2656
	global_load_dwordx4 v[228:231], v[166:167], off offset:2688
	global_load_dwordx4 v[232:235], v[166:167], off offset:2720
	s_waitcnt lgkmcnt(0)
	s_barrier
	s_waitcnt vmcnt(0)
	s_branch .LBB0_763

; __device__ __forceinline__ void cmp_phase(LAS unsigned char* lds, const bf16_t* __restrict__ P, const bf16_t* __restrict__ Kc, const bf16_t* __restrict__ Vc,
;                                           bf16_t* __restrict__ ocmp, unsigned long long* __restrict__ mask, int G, const int wave0) {
;     ...
;         for (int hh = 0; hh < 4; ++hh) {
;             const int head = 4 * g + hh;
;             bf16x8 qf[4];
; #pragma unroll
;             for (int ds = 0; ds < 4; ++ds) qf[ds] = *(const bf16x8*)(P + row * NPJ + C_NQ + head * 64 + 16 * ds + 8 * hi);
;             float m_run = -1e30f, l_run = 0.f;
.LBB0_763:
	s_lshl_b32 s6, s9, 6
	s_add_i32 s80, s6, s10
	v_lshl_add_u64 v[0:1], s[80:81], 1, v[86:87]
	v_swap_b32 v130, v146
	v_swap_b32 v131, v147
	v_swap_b32 v132, v148
	v_swap_b32 v133, v149
	v_swap_b32 v134, v150
	v_swap_b32 v135, v151
	v_swap_b32 v136, v152
	v_swap_b32 v137, v153
	v_swap_b32 v138, v154
	v_swap_b32 v139, v155
	v_swap_b32 v140, v156
	v_swap_b32 v141, v157
	v_swap_b32 v142, v158
	v_swap_b32 v143, v159
	v_swap_b32 v144, v160
	v_swap_b32 v145, v161
	v_swap_b32 v146, v200
	v_swap_b32 v147, v201
	v_swap_b32 v148, v202
	v_swap_b32 v149, v203
	v_swap_b32 v150, v204
	v_swap_b32 v151, v205
	v_swap_b32 v152, v206
	v_swap_b32 v153, v207
	v_swap_b32 v154, v208
	v_swap_b32 v155, v209
	v_swap_b32 v156, v210
	v_swap_b32 v157, v211
	v_swap_b32 v158, v216
	v_swap_b32 v159, v217
	v_swap_b32 v160, v218
	v_swap_b32 v161, v219
	v_swap_b32 v200, v220
	v_swap_b32 v201, v221
	v_swap_b32 v202, v222
	v_swap_b32 v203, v223
	v_swap_b32 v204, v224
	v_swap_b32 v205, v225
	v_swap_b32 v206, v226
	v_swap_b32 v207, v227
	v_swap_b32 v208, v228
	v_swap_b32 v209, v229
	v_swap_b32 v210, v230
	v_swap_b32 v211, v231
	v_swap_b32 v216, v232
	v_swap_b32 v217, v233
	v_swap_b32 v218, v234
	v_swap_b32 v219, v235
	v_mov_b32_e32 v64, v130
	v_mov_b32_e32 v65, v131
	v_mov_b32_e32 v66, v132
	v_mov_b32_e32 v67, v133
	v_mov_b32_e32 v68, v134
	v_mov_b32_e32 v69, v135
	v_mov_b32_e32 v70, v136
	v_mov_b32_e32 v71, v137
	v_mov_b32_e32 v72, v138
	v_mov_b32_e32 v73, v139
	v_mov_b32_e32 v74, v140
	v_mov_b32_e32 v75, v141
	v_mov_b32_e32 v76, v142
	v_mov_b32_e32 v77, v143
	v_mov_b32_e32 v78, v144
	v_mov_b32_e32 v79, v145
	v_mov_b32_e32 v33, 0
	v_mov_b32_e32 v34, 0xf149f2ca
	v_mov_b32_e32 v32, v100
	s_mov_b32 s6, 0

; __device__ __forceinline__ int crow(int r, int hi) { return (r & 3) + 8 * (r >> 2) + 4 * hi; }
; __device__ __forceinline__ void cmp_phase(LAS unsigned char* lds, const bf16_t* __restrict__ P, const bf16_t* __restrict__ Kc, const bf16_t* __restrict__ Vc,
;                                           bf16_t* __restrict__ ocmp, unsigned long long* __restrict__ mask, int G, const int wave0) {
;     ...
;                 for (int hh = 0; hh < 4; ++hh) {
;                     const int head = 4 * g + hh;
;                     bf16x8 qf[4];
; #pragma unroll
;                     for (int ds = 0; ds < 4; ++ds) qf[ds] = *(const bf16x8*)(P + row * NPJ + C_NQ + head * 64 + 16 * ds + 8 * hi);
;                     CMP_QK(c)
;                     const float m_h = mi[(hh * 32 + r32) * 2], i_h = mi[(hh * 32 + r32) * 2 + 1];
;                     if (16 * (64 * c + 63) + 31 > tw0) {
; #pragma unroll
;                         for (int r = 0; r < 16; ++r) {
;                             const int nc = 64 * c + crow(r, hi);
;                             p0[r] = (16 * nc + 31 <= tq) ? p0[r] : -INFINITY; p1[r] = (16 * (nc + 32) + 31 <= tq) ? p1[r] : -INFINITY;
;                         }
.LBB0_780:
	v_swap_b32 v130, v146
	v_swap_b32 v131, v147
	v_swap_b32 v132, v148
	v_swap_b32 v133, v149
	v_swap_b32 v134, v150
	v_swap_b32 v135, v151
	v_swap_b32 v136, v152
	v_swap_b32 v137, v153
	v_swap_b32 v138, v154
	v_swap_b32 v139, v155
	v_swap_b32 v140, v156
	v_swap_b32 v141, v157
	v_swap_b32 v142, v158
	v_swap_b32 v143, v159
	v_swap_b32 v144, v160
	v_swap_b32 v145, v161
	v_swap_b32 v146, v200
	v_swap_b32 v147, v201
	v_swap_b32 v148, v202
	v_swap_b32 v149, v203
	v_swap_b32 v150, v204
	v_swap_b32 v151, v205
	v_swap_b32 v152, v206
	v_swap_b32 v153, v207
	v_swap_b32 v154, v208
	v_swap_b32 v155, v209
	v_swap_b32 v156, v210
	v_swap_b32 v157, v211
	v_swap_b32 v158, v216
	v_swap_b32 v159, v217
	v_swap_b32 v160, v218
	v_swap_b32 v161, v219
	v_swap_b32 v200, v220
	v_swap_b32 v201, v221
	v_swap_b32 v202, v222
	v_swap_b32 v203, v223
	v_swap_b32 v204, v224
	v_swap_b32 v205, v225
	v_swap_b32 v206, v226
	v_swap_b32 v207, v227
	v_swap_b32 v208, v228
	v_swap_b32 v209, v229
	v_swap_b32 v210, v230
	v_swap_b32 v211, v231
	v_swap_b32 v216, v232
	v_swap_b32 v217, v233
	v_swap_b32 v218, v234
	v_swap_b32 v219, v235
	v_add_u32_e32 v90, s74, v92
	v_add_u32_e32 v90, 0x21400, v90
	ds_read_b64 v[90:91], v90
	s_andn2_b64 vcc, exec, s[84:85]
	s_waitcnt lgkmcnt(8)
	v_mfma_f32_32x32x16_bf16 v[16:31], v[32:35], v[130:133], 0
	s_waitcnt lgkmcnt(6)
	v_mfma_f32_32x32x16_bf16 v[0:15], v[40:43], v[130:133], 0
	v_mfma_f32_32x32x16_bf16 v[16:31], v[36:39], v[134:137], v[16:31]
	s_waitcnt lgkmcnt(5)
	v_mfma_f32_32x32x16_bf16 v[0:15], v[44:47], v[134:137], v[0:15]
	s_waitcnt lgkmcnt(4)
	v_mfma_f32_32x32x16_bf16 v[16:31], v[48:51], v[138:141], v[16:31]
	s_waitcnt lgkmcnt(2)
	v_mfma_f32_32x32x16_bf16 v[0:15], v[56:59], v[138:141], v[0:15]
	v_mfma_f32_32x32x16_bf16 v[16:31], v[52:55], v[142:145], v[16:31]
	s_waitcnt lgkmcnt(1)
	v_mfma_f32_32x32x16_bf16 v[0:15], v[60:63], v[142:145], v[0:15]
	s_cbranch_vccnz .LBB0_779
	s_nop 8
	v_cndmask_b32_e64 v16, v16, v249, s[4:5]
	s_nop 0
	v_cndmask_b32_e64 v0, v0, v249, s[6:7]
	v_cndmask_b32_e64 v17, v17, v249, s[8:9]
	v_cndmask_b32_e64 v1, v1, v249, s[10:11]
	v_cndmask_b32_e64 v18, v18, v249, s[12:13]
	v_cndmask_b32_e64 v2, v2, v249, s[14:15]
	v_cndmask_b32_e64 v19, v19, v249, s[16:17]
	v_cndmask_b32_e64 v3, v3, v249, s[18:19]
	v_cndmask_b32_e64 v20, v20, v249, s[20:21]
	v_cndmask_b32_e64 v4, v4, v249, s[22:23]
	v_cndmask_b32_e64 v21, v21, v249, s[24:25]
	v_cndmask_b32_e64 v5, v5, v249, s[26:27]
	v_cndmask_b32_e64 v22, v22, v249, s[28:29]
	v_cndmask_b32_e64 v6, v6, v249, s[30:31]
	v_cndmask_b32_e64 v23, v23, v249, s[34:35]
	v_cndmask_b32_e64 v7, v7, v249, s[36:37]
	v_cndmask_b32_e64 v24, v24, v249, s[38:39]
	v_cndmask_b32_e64 v8, v8, v249, s[40:41]
	v_cndmask_b32_e64 v25, v25, v249, s[42:43]
	v_cndmask_b32_e64 v9, v9, v249, s[44:45]
	v_cndmask_b32_e64 v26, v26, v249, s[46:47]
	v_cndmask_b32_e64 v10, v10, v249, s[48:49]
	v_cndmask_b32_e64 v27, v27, v249, s[50:51]
	v_cndmask_b32_e64 v11, v11, v249, s[52:53]
	v_cndmask_b32_e64 v28, v28, v249, s[54:55]
	v_cndmask_b32_e64 v12, v12, v249, s[56:57]
	v_cndmask_b32_e64 v29, v29, v249, s[58:59]
	v_cndmask_b32_e64 v13, v13, v249, s[60:61]
	v_cndmask_b32_e64 v30, v30, v249, s[62:63]
	v_cndmask_b32_e64 v14, v14, v249, s[64:65]
	v_cndmask_b32_e64 v31, v31, v249, s[66:67]
	v_cndmask_b32_e64 v15, v15, v249, s[68:69]
	s_branch .LBB0_779
